# clique barrier also for out-proj->scores in the mLSTM/GLA layers (S5 layer keeps the grid barrier there: its out GEMM reads Z which XO overlaps)
# speedup vs baseline: 1.0150x; 1.0062x over previous
; DEVI unsigned xb_ld(unsigned* p)              { return __hip_atomic_load(p, __ATOMIC_RELAXED, __HIP_MEMORY_SCOPE_AGENT); }
; DEVI unsigned xb_add(unsigned* p, unsigned v) { return __hip_atomic_fetch_add(p, v, __ATOMIC_RELAXED, __HIP_MEMORY_SCOPE_AGENT); }
; #define XB_SPIN(cond, bar) do { unsigned _sp = 0; while (cond) { __builtin_amdgcn_s_sleep(1); \
;     if ((++_sp & 255u) == 0u) { if (xb_ld(&(bar)[XB_TMO])) break; if (_sp > XB_SPIN_CAP) { atomicAdd(&(bar)[XB_TMO], 1u); break; } } } } while (0)
; DEVI void xcd_barrier(const XcdBarrier& b) {
;     asm volatile("s_waitcnt vmcnt(0)" ::: "memory");
;     __syncthreads();
;     if (threadIdx.x == 0) {
;         unsigned* bar = b.bar;
;         __builtin_amdgcn_s_waitcnt(0);
;         unsigned nloc = b.st[0], nx = b.st[1];
;         if (nloc == 0u) { xcd_barrier_complete(bar, b.x, nloc, nx); b.st[0] = nloc; b.st[1] = nx; }
;         const unsigned old = xb_add(&bar[XB_XSUB(b.x)], 1u);
;         const unsigned gen = old / nloc;
;         if (old + 1u == (gen + 1u) * nloc) {
;             __builtin_amdgcn_fence(__ATOMIC_RELEASE, "agent");
;             asm volatile("s_waitcnt vmcnt(0)" ::: "memory");
;             const unsigned og = xb_add(&bar[XB_TOP], 1u);
;             const unsigned tg = og / nx;
;             if (og + 1u == (tg + 1u) * nx) xb_add(&bar[XB_TOPGEN], 1u);
;             else XB_SPIN(xb_ld(&bar[XB_TOPGEN]) == tg, bar);
;             __builtin_amdgcn_fence(__ATOMIC_ACQUIRE, "agent");
;             xb_add(&bar[XB_XGEN(b.x)], 1u);
;             asm volatile("s_waitcnt vmcnt(0)" ::: "memory");
;         } else {
;             XB_SPIN(xb_ld(&bar[XB_XGEN(b.x)]) == gen, bar);
;             __builtin_amdgcn_fence(__ATOMIC_ACQUIRE, "agent");
;             asm volatile("s_waitcnt vmcnt(0)" ::: "memory");
;         }
;     }
;     __syncthreads();
; }
; __global__ void __launch_bounds__(512, 2) fwd_megakernel(Params p) {
;     ...
;         xcd_barrier(xb);
.LBB0_1439:
	s_waitcnt vmcnt(0)
	s_waitcnt lgkmcnt(0)
	s_barrier
	s_mov_b64 s[2:3], exec
	v_readlane_b32 s0, v251, 6
	v_readlane_b32 s1, v251, 7
	s_and_b64 s[0:1], s[2:3], s[0:1]
	s_mov_b64 exec, s[0:1]
	s_cbranch_execz .LBB0_1487
	v_mov_b32_e32 v1, 0x26008
	ds_read_b32 v1, v1
	s_bfe_u32 s4, s33, 0x30003
	s_lshl_b32 s4, s4, 5
	s_addk_i32 s4, 0x800
	s_mov_b32 s5, 0
	s_waitcnt lgkmcnt(0)
	v_readfirstlane_b32 s6, v1
	v_lshl_add_u64 v[0:1], v[156:157], 0, s[4:5]
	v_mov_b32_e32 v2, 1
	v_readlane_b32 s7, v254, 2
	s_nop 0
	s_cmp_eq_u32 s7, 2
	s_cselect_b32 s6, 0, s6
	s_cmp_eq_u32 s6, 0
	s_cbranch_scc1 .Lxq_slow_0
	global_atomic_add v3, v[0:1], v2, off sc0
	s_mov_b32 s7, 0
	s_waitcnt vmcnt(0)
	v_or_b32_e32 v3, 3, v3
	v_add_u32_e32 v3, 1, v3
